# v50 without the packed mul/add fusion in the P12 epilogue (measured slower there) and a 12-byte pad at kernel entry that keeps the code placement of the timed experiment build
# speedup vs baseline: 1.0066x; 1.0066x over previous
_Z10fwd_kernel6Params:
	s_mov_b32 s96, s2
	s_nop 0
	s_nop 0
	s_nop 0
	s_load_dword s2, s[0:1], 0xf0
	s_load_dwordx2 s[22:23], s[0:1], 0xe8
	s_load_dwordx8 s[24:31], s[0:1], 0xc0
	v_and_b32_e32 v170, 0x3ff, v0
	v_cmp_gt_u32_e32 vcc, 4, v170
	s_waitcnt lgkmcnt(0)
	v_writelane_b32 v254, s2, 0
	v_readfirstlane_b32 s2, v170
	s_nop 1
	v_writelane_b32 v254, s2, 1
	s_add_u32 s2, s0, 0xe8
	s_addc_u32 s3, s1, 0
	v_writelane_b32 v254, s2, 2
	s_nop 1
	v_writelane_b32 v254, s3, 3
	s_and_saveexec_b64 s[2:3], vcc
	v_lshl_add_u32 v1, v170, 2, 0
	v_add_u32_e32 v1, 0x25ff0, v1
	v_mov_b32_e32 v2, 0
	ds_write_b32 v1, v2
	s_or_b64 exec, exec, s[2:3]
	s_load_dwordx2 s[84:85], s[0:1], 0xe0
	s_waitcnt lgkmcnt(0)
	s_barrier
	s_getreg_b32 s2, hwreg(HW_REG_XCC_ID, 0, 4)
	s_and_b32 s97, s2, 15
	v_cmp_eq_u32_e64 s[4:5], 0, v170
	s_mov_b64 s[2:3], exec
	s_nop 0
	v_writelane_b32 v254, s4, 4
	s_nop 1
	v_writelane_b32 v254, s5, 5
	s_and_b64 s[4:5], s[2:3], s[4:5]
	s_mov_b64 exec, s[4:5]
	s_cbranch_execz .LBB0_6
	s_mov_b64 s[6:7], exec
	v_mbcnt_lo_u32_b32 v1, s6, 0
	v_mbcnt_hi_u32_b32 v1, s7, v1
	v_cmp_eq_u32_e32 vcc, 0, v1
	s_and_saveexec_b64 s[4:5], vcc
	s_cbranch_execz .LBB0_5
	s_lshl_b32 s8, s97, 8
	s_bcnt1_i32_b64 s6, s[6:7]
	v_mov_b32_e32 v2, s8
	v_mov_b32_e32 v3, s6
	global_atomic_add v2, v2, v3, s[30:31] offset:1024 sc0

.Ldfr_p12_b:
	s_setprio 0
	s_ashr_i32 s9, s16, 3
	s_mul_hi_i32 s11, s9, 0x5800
	s_mulk_i32 s9, 0x5800
	s_add_u32 s9, s48, s9
	s_addc_u32 s11, s49, s11
	s_lshl_b32 s18, s17, 8
	s_ashr_i32 s19, s18, 31
	s_lshl_b64 s[18:19], s[18:19], 2
	v_lshl_add_u32 v180, s16, 8, v1
	s_add_u32 s18, s9, s18
	s_addc_u32 s19, s11, s19
	v_lshlrev_b32_e32 v130, 2, v156
	v_ashrrev_i32_e32 v181, 31, v180
	v_mov_b32_e32 v142, v236
	v_mov_b32_e32 v143, v237
	v_mov_b32_e32 v144, v238
	v_mov_b32_e32 v145, v239
	v_lshl_add_u64 v[182:183], v[180:181], 2, s[4:5]
	v_mov_b32_e32 v190, v228
	v_mov_b32_e32 v138, v240
	v_mov_b32_e32 v139, v241
	v_mov_b32_e32 v140, v242
	v_mov_b32_e32 v141, v243
	v_mov_b32_e32 v134, v244
	v_mov_b32_e32 v135, v245
	v_mov_b32_e32 v136, v246
	v_mov_b32_e32 v137, v247
	s_nop 0
	v_mov_b32_e32 v130, v248
	v_mov_b32_e32 v131, v249
	v_mov_b32_e32 v132, v250
	v_mov_b32_e32 v133, v251
	v_or_b32_e32 v192, 16, v180
	v_ashrrev_i32_e32 v193, 31, v192
	v_lshl_add_u64 v[168:169], v[192:193], 2, s[4:5]
	v_mov_b32_e32 v194, v229
	v_or_b32_e32 v188, 32, v180
	v_or_b32_e32 v184, 48, v180
	v_mov_b64_e32 v[166:167], s[0:1]
	v_add_u32_e32 v178, 0x90, v180
	v_add_u32_e32 v174, 0xa0, v180
	v_add_u32_e32 v168, 0xb0, v180
	v_ashrrev_i32_e32 v189, 31, v188
	v_ashrrev_i32_e32 v185, 31, v184
	v_add_u32_e32 v193, 0x80, v180
	v_mad_i64_i32 v[196:197], s[18:19], v180, s56, v[166:167]
	v_ashrrev_i32_e32 v179, 31, v178
	v_ashrrev_i32_e32 v175, 31, v174
	v_ashrrev_i32_e32 v169, 31, v168
	v_lshl_add_u64 v[180:181], v[188:189], 2, s[4:5]
	v_lshl_add_u64 v[186:187], v[184:185], 2, s[4:5]
	v_lshl_add_u64 v[198:199], v[178:179], 2, s[4:5]
	v_lshl_add_u64 v[200:201], v[174:175], 2, s[4:5]
	v_lshl_add_u64 v[202:203], v[168:169], 2, s[4:5]
	v_mov_b32_e32 v204, v233
	s_nop 0
	v_mov_b32_e32 v186, v234
	s_nop 0
	v_mov_b32_e32 v180, v255
	s_nop 0
	v_mov_b32_e32 v182, v235
	s_lshl_b32 s16, s17, 7
	s_ashr_i32 s17, s16, 31
	s_lshl_b64 s[16:17], s[16:17], 1
	v_lshlrev_b32_e32 v154, 1, v156
	v_lshl_add_u64 v[196:197], v[196:197], 0, s[16:17]
	s_and_b64 vcc, exec, s[2:3]
	s_mov_b64 s[34:35], s[14:15]
	s_mov_b64 s[24:25], s[12:13]
	v_pk_fma_f32 v[118:119], v[118:119], v[190:191], v[138:139] op_sel_hi:[1,0,1]
	v_pk_fma_f32 v[126:127], v[126:127], v[190:191], v[142:143] op_sel_hi:[1,0,1]
	v_pk_fma_f32 v[128:129], v[128:129], v[190:191], v[144:145] op_sel_hi:[1,0,1]
	v_pk_fma_f32 v[122:123], v[122:123], v[190:191], v[134:135] op_sel_hi:[1,0,1]
	v_pk_fma_f32 v[124:125], v[124:125], v[190:191], v[136:137] op_sel_hi:[1,0,1]
	v_mul_f32_e32 v169, 0xbfb8aa3b, v126
	v_mul_f32_e32 v175, 0xbfb8aa3b, v127
	v_mul_f32_e32 v179, 0xbfb8aa3b, v128
	v_mul_f32_e32 v181, 0xbfb8aa3b, v129
	v_mul_f32_e32 v183, 0xbfb8aa3b, v122
	v_mul_f32_e32 v185, 0xbfb8aa3b, v123
	v_mul_f32_e32 v187, 0xbfb8aa3b, v124
	v_mul_f32_e32 v189, 0xbfb8aa3b, v125
	v_exp_f32_e32 v169, v169
	v_exp_f32_e32 v175, v175
	v_exp_f32_e32 v179, v179
	v_exp_f32_e32 v181, v181
	v_exp_f32_e32 v183, v183
	v_exp_f32_e32 v185, v185
	v_exp_f32_e32 v187, v187
	v_exp_f32_e32 v189, v189
	v_add_f32_e32 v169, 1.0, v169
	v_add_f32_e32 v175, 1.0, v175
	v_add_f32_e32 v179, 1.0, v179
	v_add_f32_e32 v181, 1.0, v181
	v_add_f32_e32 v183, 1.0, v183
	v_add_f32_e32 v185, 1.0, v185
	v_add_f32_e32 v187, 1.0, v187
	v_add_f32_e32 v189, 1.0, v189
	v_pk_fma_f32 v[120:121], v[120:121], v[190:191], v[140:141] op_sel_hi:[1,0,1]
	v_pk_fma_f32 v[114:115], v[114:115], v[190:191], v[130:131] op_sel_hi:[1,0,1]
	v_pk_fma_f32 v[116:117], v[116:117], v[190:191], v[132:133] op_sel_hi:[1,0,1]
	v_rcp_f32_e32 v190, v169
	v_rcp_f32_e32 v191, v175
	v_rcp_f32_e32 v198, v179
	v_rcp_f32_e32 v199, v181
	v_rcp_f32_e32 v200, v183
	v_rcp_f32_e32 v201, v185
	v_rcp_f32_e32 v202, v187
	v_rcp_f32_e32 v203, v189
	v_pk_mul_f32 v[126:127], v[126:127], v[190:191]
	v_pk_mul_f32 v[128:129], v[128:129], v[198:199]
	v_pk_mul_f32 v[122:123], v[122:123], v[200:201]
	v_pk_mul_f32 v[124:125], v[124:125], v[202:203]
	v_pk_mul_f32 v[118:119], v[118:119], v[126:127]
	v_pk_mul_f32 v[120:121], v[120:121], v[128:129]
	v_pk_mul_f32 v[122:123], v[114:115], v[122:123]
	v_pk_mul_f32 v[124:125], v[116:117], v[124:125]
	v_pk_fma_f32 v[110:111], v[110:111], v[194:195], v[142:143] op_sel_hi:[1,0,1]
	v_lshl_add_u64 v[126:127], v[196:197], 0, v[154:155]
	v_cvt_pk_bf16_f32 v114, v118, v119
	v_cvt_pk_bf16_f32 v115, v120, v121
	v_cvt_pk_bf16_f32 v116, v122, v123
	v_cvt_pk_bf16_f32 v117, v124, v125
	v_mul_f32_e32 v118, 0xbfb8aa3b, v110
	v_mul_f32_e32 v119, 0xbfb8aa3b, v111
	v_pk_fma_f32 v[112:113], v[112:113], v[194:195], v[144:145] op_sel_hi:[1,0,1]
	v_exp_f32_e32 v118, v118
	v_exp_f32_e32 v119, v119
	global_store_dwordx4 v[126:127], v[114:117], off nt
	v_pk_fma_f32 v[102:103], v[102:103], v[194:195], v[138:139] op_sel_hi:[1,0,1]
	v_pk_fma_f32 v[106:107], v[106:107], v[194:195], v[134:135] op_sel_hi:[1,0,1]
	v_mul_f32_e32 v116, 0xbfb8aa3b, v112
	v_mul_f32_e32 v117, 0xbfb8aa3b, v113
	v_exp_f32_e32 v116, v116
	v_exp_f32_e32 v117, v117
	v_add_f32_e32 v114, 1.0, v118
	v_add_f32_e32 v115, 1.0, v119
	v_rcp_f32_e32 v114, v114
	v_rcp_f32_e32 v115, v115
	v_add_f32_e32 v116, 1.0, v116
	v_add_f32_e32 v117, 1.0, v117
	v_rcp_f32_e32 v116, v116
	v_rcp_f32_e32 v117, v117
	v_pk_mul_f32 v[110:111], v[110:111], v[114:115]
	v_pk_fma_f32 v[104:105], v[104:105], v[194:195], v[140:141] op_sel_hi:[1,0,1]
	v_pk_mul_f32 v[102:103], v[102:103], v[110:111]
	v_pk_mul_f32 v[110:111], v[112:113], v[116:117]
	v_mul_f32_e32 v112, 0xbfb8aa3b, v106
	v_mul_f32_e32 v113, 0xbfb8aa3b, v107
	v_exp_f32_e32 v112, v112
	v_exp_f32_e32 v113, v113
	v_pk_fma_f32 v[108:109], v[108:109], v[194:195], v[136:137] op_sel_hi:[1,0,1]
	v_pk_mul_f32 v[104:105], v[104:105], v[110:111]
	v_add_f32_e32 v110, 1.0, v112
	v_add_f32_e32 v111, 1.0, v113
	v_mul_f32_e32 v112, 0xbfb8aa3b, v108
	v_mul_f32_e32 v113, 0xbfb8aa3b, v109
	v_exp_f32_e32 v112, v112
	v_exp_f32_e32 v113, v113
	v_rcp_f32_e32 v110, v110
	v_rcp_f32_e32 v111, v111
	v_add_f32_e32 v112, 1.0, v112
	v_add_f32_e32 v113, 1.0, v113
	v_rcp_f32_e32 v112, v112
	v_rcp_f32_e32 v113, v113
	v_pk_mul_f32 v[106:107], v[106:107], v[110:111]
	v_pk_fma_f32 v[98:99], v[98:99], v[194:195], v[130:131] op_sel_hi:[1,0,1]
	v_pk_fma_f32 v[100:101], v[100:101], v[194:195], v[132:133] op_sel_hi:[1,0,1]
	v_pk_mul_f32 v[106:107], v[98:99], v[106:107]
	v_pk_mul_f32 v[98:99], v[108:109], v[112:113]
	v_pk_fma_f32 v[94:95], v[94:95], v[204:205], v[142:143] op_sel_hi:[1,0,1]
	v_pk_mul_f32 v[108:109], v[100:101], v[98:99]
	v_mad_i64_i32 v[98:99], s[18:19], v192, s56, v[166:167]
	v_lshl_add_u64 v[98:99], v[98:99], 0, s[16:17]
	v_lshl_add_u64 v[110:111], v[98:99], 0, v[154:155]
	v_cvt_pk_bf16_f32 v98, v102, v103
	v_cvt_pk_bf16_f32 v99, v104, v105
	v_cvt_pk_bf16_f32 v100, v106, v107
	v_cvt_pk_bf16_f32 v101, v108, v109
	v_mul_f32_e32 v102, 0xbfb8aa3b, v94
	v_mul_f32_e32 v103, 0xbfb8aa3b, v95
	v_pk_fma_f32 v[96:97], v[96:97], v[204:205], v[144:145] op_sel_hi:[1,0,1]
	v_exp_f32_e32 v102, v102
	v_exp_f32_e32 v103, v103
	global_store_dwordx4 v[110:111], v[98:101], off nt
	v_pk_fma_f32 v[86:87], v[86:87], v[204:205], v[138:139] op_sel_hi:[1,0,1]
	v_pk_fma_f32 v[90:91], v[90:91], v[204:205], v[134:135] op_sel_hi:[1,0,1]
	v_mul_f32_e32 v100, 0xbfb8aa3b, v96
	v_mul_f32_e32 v101, 0xbfb8aa3b, v97
	v_exp_f32_e32 v100, v100
	v_exp_f32_e32 v101, v101
	v_add_f32_e32 v98, 1.0, v102
	v_add_f32_e32 v99, 1.0, v103
	v_rcp_f32_e32 v98, v98
	v_rcp_f32_e32 v99, v99
	v_add_f32_e32 v100, 1.0, v100
	v_add_f32_e32 v101, 1.0, v101
	v_rcp_f32_e32 v100, v100
	v_rcp_f32_e32 v101, v101
	v_pk_mul_f32 v[94:95], v[94:95], v[98:99]
	v_pk_fma_f32 v[88:89], v[88:89], v[204:205], v[140:141] op_sel_hi:[1,0,1]
	v_pk_mul_f32 v[86:87], v[86:87], v[94:95]
	v_pk_mul_f32 v[94:95], v[96:97], v[100:101]
	v_mul_f32_e32 v96, 0xbfb8aa3b, v90
	v_mul_f32_e32 v97, 0xbfb8aa3b, v91
	v_exp_f32_e32 v96, v96
	v_exp_f32_e32 v97, v97
	v_pk_fma_f32 v[92:93], v[92:93], v[204:205], v[136:137] op_sel_hi:[1,0,1]
	v_pk_mul_f32 v[88:89], v[88:89], v[94:95]
	v_add_f32_e32 v94, 1.0, v96
	v_add_f32_e32 v95, 1.0, v97
	v_mul_f32_e32 v96, 0xbfb8aa3b, v92
	v_mul_f32_e32 v97, 0xbfb8aa3b, v93
	v_exp_f32_e32 v96, v96
	v_exp_f32_e32 v97, v97
	v_rcp_f32_e32 v94, v94
	v_rcp_f32_e32 v95, v95
	v_add_f32_e32 v96, 1.0, v96
	v_add_f32_e32 v97, 1.0, v97
	v_rcp_f32_e32 v96, v96
	v_rcp_f32_e32 v97, v97
	v_pk_mul_f32 v[90:91], v[90:91], v[94:95]
	v_pk_fma_f32 v[82:83], v[82:83], v[204:205], v[130:131] op_sel_hi:[1,0,1]
	v_pk_fma_f32 v[84:85], v[84:85], v[204:205], v[132:133] op_sel_hi:[1,0,1]
	v_pk_mul_f32 v[90:91], v[82:83], v[90:91]
	v_pk_mul_f32 v[82:83], v[92:93], v[96:97]
	v_pk_fma_f32 v[78:79], v[78:79], v[186:187], v[142:143] op_sel_hi:[1,0,1]
	v_pk_mul_f32 v[92:93], v[84:85], v[82:83]
	v_mad_i64_i32 v[82:83], s[18:19], v188, s56, v[166:167]
	v_lshl_add_u64 v[82:83], v[82:83], 0, s[16:17]
	v_lshl_add_u64 v[94:95], v[82:83], 0, v[154:155]
	v_cvt_pk_bf16_f32 v82, v86, v87
	v_cvt_pk_bf16_f32 v83, v88, v89
	v_cvt_pk_bf16_f32 v84, v90, v91
	v_cvt_pk_bf16_f32 v85, v92, v93
	v_mul_f32_e32 v86, 0xbfb8aa3b, v78
	v_mul_f32_e32 v87, 0xbfb8aa3b, v79
	v_pk_fma_f32 v[80:81], v[80:81], v[186:187], v[144:145] op_sel_hi:[1,0,1]
	v_exp_f32_e32 v86, v86
	v_exp_f32_e32 v87, v87
	global_store_dwordx4 v[94:95], v[82:85], off nt
	v_pk_fma_f32 v[70:71], v[70:71], v[186:187], v[138:139] op_sel_hi:[1,0,1]
	v_pk_fma_f32 v[74:75], v[74:75], v[186:187], v[134:135] op_sel_hi:[1,0,1]
	v_mul_f32_e32 v84, 0xbfb8aa3b, v80
	v_mul_f32_e32 v85, 0xbfb8aa3b, v81
	v_exp_f32_e32 v84, v84
	v_exp_f32_e32 v85, v85
	v_add_f32_e32 v82, 1.0, v86
	v_add_f32_e32 v83, 1.0, v87
	v_rcp_f32_e32 v82, v82
	v_rcp_f32_e32 v83, v83
	v_add_f32_e32 v84, 1.0, v84
	v_add_f32_e32 v85, 1.0, v85
	v_rcp_f32_e32 v84, v84
	v_rcp_f32_e32 v85, v85
	v_pk_mul_f32 v[78:79], v[78:79], v[82:83]
	v_pk_fma_f32 v[72:73], v[72:73], v[186:187], v[140:141] op_sel_hi:[1,0,1]
	v_pk_mul_f32 v[70:71], v[70:71], v[78:79]
	v_pk_mul_f32 v[78:79], v[80:81], v[84:85]
	v_mul_f32_e32 v80, 0xbfb8aa3b, v74
	v_mul_f32_e32 v81, 0xbfb8aa3b, v75
	v_exp_f32_e32 v80, v80
	v_exp_f32_e32 v81, v81
	v_pk_fma_f32 v[76:77], v[76:77], v[186:187], v[136:137] op_sel_hi:[1,0,1]
	v_pk_mul_f32 v[72:73], v[72:73], v[78:79]
	v_add_f32_e32 v78, 1.0, v80
	v_add_f32_e32 v79, 1.0, v81
	v_mul_f32_e32 v80, 0xbfb8aa3b, v76
	v_mul_f32_e32 v81, 0xbfb8aa3b, v77
	v_exp_f32_e32 v80, v80
	v_exp_f32_e32 v81, v81
	v_rcp_f32_e32 v78, v78
	v_rcp_f32_e32 v79, v79
	v_add_f32_e32 v80, 1.0, v80
	v_add_f32_e32 v81, 1.0, v81
	v_rcp_f32_e32 v80, v80
	v_rcp_f32_e32 v81, v81
	v_pk_mul_f32 v[74:75], v[74:75], v[78:79]
	v_pk_fma_f32 v[66:67], v[66:67], v[186:187], v[130:131] op_sel_hi:[1,0,1]
	v_pk_fma_f32 v[68:69], v[68:69], v[186:187], v[132:133] op_sel_hi:[1,0,1]
	v_pk_mul_f32 v[74:75], v[66:67], v[74:75]
	v_pk_mul_f32 v[66:67], v[76:77], v[80:81]
	v_pk_fma_f32 v[62:63], v[62:63], v[182:183], v[142:143] op_sel_hi:[1,0,1]
	v_pk_mul_f32 v[76:77], v[68:69], v[66:67]
	v_mad_i64_i32 v[66:67], s[18:19], v184, s56, v[166:167]
	v_lshl_add_u64 v[66:67], v[66:67], 0, s[16:17]
	v_lshl_add_u64 v[78:79], v[66:67], 0, v[154:155]
	v_cvt_pk_bf16_f32 v66, v70, v71
	v_cvt_pk_bf16_f32 v67, v72, v73
	v_cvt_pk_bf16_f32 v68, v74, v75
	v_cvt_pk_bf16_f32 v69, v76, v77
	v_mul_f32_e32 v70, 0xbfb8aa3b, v62
	v_mul_f32_e32 v71, 0xbfb8aa3b, v63
	v_pk_fma_f32 v[64:65], v[64:65], v[182:183], v[144:145] op_sel_hi:[1,0,1]
	v_exp_f32_e32 v70, v70
	v_exp_f32_e32 v71, v71
	global_store_dwordx4 v[78:79], v[66:69], off nt
	v_pk_fma_f32 v[54:55], v[54:55], v[182:183], v[138:139] op_sel_hi:[1,0,1]
	v_pk_fma_f32 v[58:59], v[58:59], v[182:183], v[134:135] op_sel_hi:[1,0,1]
	v_mul_f32_e32 v68, 0xbfb8aa3b, v64
	v_mul_f32_e32 v69, 0xbfb8aa3b, v65
	v_exp_f32_e32 v68, v68
	v_exp_f32_e32 v69, v69
	v_add_f32_e32 v66, 1.0, v70
	v_add_f32_e32 v67, 1.0, v71
	v_rcp_f32_e32 v66, v66
	v_rcp_f32_e32 v67, v67
	v_add_f32_e32 v68, 1.0, v68
	v_add_f32_e32 v69, 1.0, v69
	v_rcp_f32_e32 v68, v68
	v_rcp_f32_e32 v69, v69
	v_pk_mul_f32 v[62:63], v[62:63], v[66:67]
	v_pk_fma_f32 v[56:57], v[56:57], v[182:183], v[140:141] op_sel_hi:[1,0,1]
	v_pk_mul_f32 v[54:55], v[54:55], v[62:63]
	v_pk_mul_f32 v[62:63], v[64:65], v[68:69]
	v_mul_f32_e32 v64, 0xbfb8aa3b, v58
	v_mul_f32_e32 v65, 0xbfb8aa3b, v59
	v_exp_f32_e32 v64, v64
	v_exp_f32_e32 v65, v65
	v_pk_fma_f32 v[60:61], v[60:61], v[182:183], v[136:137] op_sel_hi:[1,0,1]
	v_pk_mul_f32 v[56:57], v[56:57], v[62:63]
	v_add_f32_e32 v62, 1.0, v64
	v_add_f32_e32 v63, 1.0, v65
	v_mul_f32_e32 v64, 0xbfb8aa3b, v60
	v_mul_f32_e32 v65, 0xbfb8aa3b, v61
	v_exp_f32_e32 v64, v64
	v_exp_f32_e32 v65, v65
	v_rcp_f32_e32 v62, v62
	v_rcp_f32_e32 v63, v63
	v_add_f32_e32 v64, 1.0, v64
	v_add_f32_e32 v65, 1.0, v65
	v_rcp_f32_e32 v64, v64
	v_rcp_f32_e32 v65, v65
	v_pk_mul_f32 v[58:59], v[58:59], v[62:63]
	v_pk_fma_f32 v[50:51], v[50:51], v[182:183], v[130:131] op_sel_hi:[1,0,1]
	v_pk_fma_f32 v[52:53], v[52:53], v[182:183], v[132:133] op_sel_hi:[1,0,1]
	v_pk_mul_f32 v[58:59], v[50:51], v[58:59]
	v_pk_mul_f32 v[50:51], v[60:61], v[64:65]
	v_pk_fma_f32 v[46:47], v[46:47], v[180:181], v[142:143] op_sel_hi:[1,0,1]
	v_pk_mul_f32 v[60:61], v[52:53], v[50:51]
	v_mad_i64_i32 v[50:51], s[18:19], v193, s56, v[166:167]
	v_lshl_add_u64 v[50:51], v[50:51], 0, s[16:17]
	v_lshl_add_u64 v[62:63], v[50:51], 0, v[154:155]
	v_cvt_pk_bf16_f32 v50, v54, v55
	v_cvt_pk_bf16_f32 v51, v56, v57
	v_cvt_pk_bf16_f32 v52, v58, v59
	v_cvt_pk_bf16_f32 v53, v60, v61
	v_mul_f32_e32 v54, 0xbfb8aa3b, v46
	v_mul_f32_e32 v55, 0xbfb8aa3b, v47
	v_pk_fma_f32 v[48:49], v[48:49], v[180:181], v[144:145] op_sel_hi:[1,0,1]
	v_exp_f32_e32 v54, v54
	v_exp_f32_e32 v55, v55
	global_store_dwordx4 v[62:63], v[50:53], off nt
	v_pk_fma_f32 v[38:39], v[38:39], v[180:181], v[138:139] op_sel_hi:[1,0,1]
	v_pk_fma_f32 v[42:43], v[42:43], v[180:181], v[134:135] op_sel_hi:[1,0,1]
	v_mul_f32_e32 v52, 0xbfb8aa3b, v48
	v_mul_f32_e32 v53, 0xbfb8aa3b, v49
	v_exp_f32_e32 v52, v52
	v_exp_f32_e32 v53, v53
	v_add_f32_e32 v50, 1.0, v54
	v_add_f32_e32 v51, 1.0, v55
	v_rcp_f32_e32 v50, v50
	v_rcp_f32_e32 v51, v51
	v_add_f32_e32 v52, 1.0, v52
	v_add_f32_e32 v53, 1.0, v53
	v_rcp_f32_e32 v52, v52
	v_rcp_f32_e32 v53, v53
	v_pk_mul_f32 v[46:47], v[46:47], v[50:51]
	v_pk_fma_f32 v[40:41], v[40:41], v[180:181], v[140:141] op_sel_hi:[1,0,1]
	v_pk_mul_f32 v[38:39], v[38:39], v[46:47]
	v_pk_mul_f32 v[46:47], v[48:49], v[52:53]
	v_mul_f32_e32 v48, 0xbfb8aa3b, v42
	v_mul_f32_e32 v49, 0xbfb8aa3b, v43
	v_exp_f32_e32 v48, v48
	v_exp_f32_e32 v49, v49
	v_pk_fma_f32 v[44:45], v[44:45], v[180:181], v[136:137] op_sel_hi:[1,0,1]
	v_pk_mul_f32 v[40:41], v[40:41], v[46:47]
	v_add_f32_e32 v46, 1.0, v48
	v_add_f32_e32 v47, 1.0, v49
	v_mul_f32_e32 v48, 0xbfb8aa3b, v44
	v_mul_f32_e32 v49, 0xbfb8aa3b, v45
	v_exp_f32_e32 v48, v48
	v_exp_f32_e32 v49, v49
	v_rcp_f32_e32 v46, v46
	v_rcp_f32_e32 v47, v47
	v_add_f32_e32 v48, 1.0, v48
	v_add_f32_e32 v49, 1.0, v49
	v_rcp_f32_e32 v48, v48
	v_rcp_f32_e32 v49, v49
	v_pk_mul_f32 v[42:43], v[42:43], v[46:47]
	v_pk_fma_f32 v[34:35], v[34:35], v[180:181], v[130:131] op_sel_hi:[1,0,1]
	v_pk_fma_f32 v[36:37], v[36:37], v[180:181], v[132:133] op_sel_hi:[1,0,1]
	v_pk_mul_f32 v[42:43], v[34:35], v[42:43]
	v_pk_mul_f32 v[34:35], v[44:45], v[48:49]
	v_pk_fma_f32 v[30:31], v[30:31], v[176:177], v[142:143] op_sel_hi:[1,0,1]
	v_pk_mul_f32 v[44:45], v[36:37], v[34:35]
	v_mad_i64_i32 v[34:35], s[18:19], v178, s56, v[166:167]
	v_lshl_add_u64 v[34:35], v[34:35], 0, s[16:17]
	v_lshl_add_u64 v[46:47], v[34:35], 0, v[154:155]
	v_cvt_pk_bf16_f32 v34, v38, v39
	v_cvt_pk_bf16_f32 v35, v40, v41
	v_cvt_pk_bf16_f32 v36, v42, v43
	v_cvt_pk_bf16_f32 v37, v44, v45
	v_mul_f32_e32 v38, 0xbfb8aa3b, v30
	v_mul_f32_e32 v39, 0xbfb8aa3b, v31
	v_pk_fma_f32 v[32:33], v[32:33], v[176:177], v[144:145] op_sel_hi:[1,0,1]
	v_exp_f32_e32 v38, v38
	v_exp_f32_e32 v39, v39
	global_store_dwordx4 v[46:47], v[34:37], off nt
	v_pk_fma_f32 v[22:23], v[22:23], v[176:177], v[138:139] op_sel_hi:[1,0,1]
	v_pk_fma_f32 v[26:27], v[26:27], v[176:177], v[134:135] op_sel_hi:[1,0,1]
	v_mul_f32_e32 v36, 0xbfb8aa3b, v32
	v_mul_f32_e32 v37, 0xbfb8aa3b, v33
	v_exp_f32_e32 v36, v36
	v_exp_f32_e32 v37, v37
	v_add_f32_e32 v34, 1.0, v38
	v_add_f32_e32 v35, 1.0, v39
	v_rcp_f32_e32 v34, v34
	v_rcp_f32_e32 v35, v35
	v_add_f32_e32 v36, 1.0, v36
	v_add_f32_e32 v37, 1.0, v37
	v_rcp_f32_e32 v36, v36
	v_rcp_f32_e32 v37, v37
	v_pk_mul_f32 v[30:31], v[30:31], v[34:35]
	v_pk_fma_f32 v[24:25], v[24:25], v[176:177], v[140:141] op_sel_hi:[1,0,1]
	v_pk_mul_f32 v[22:23], v[22:23], v[30:31]
	v_pk_mul_f32 v[30:31], v[32:33], v[36:37]
	v_mul_f32_e32 v32, 0xbfb8aa3b, v26
	v_mul_f32_e32 v33, 0xbfb8aa3b, v27
	v_exp_f32_e32 v32, v32
	v_exp_f32_e32 v33, v33
	v_pk_fma_f32 v[28:29], v[28:29], v[176:177], v[136:137] op_sel_hi:[1,0,1]
	v_pk_mul_f32 v[24:25], v[24:25], v[30:31]
	v_add_f32_e32 v30, 1.0, v32
	v_add_f32_e32 v31, 1.0, v33
	v_mul_f32_e32 v32, 0xbfb8aa3b, v28
	v_mul_f32_e32 v33, 0xbfb8aa3b, v29
	v_exp_f32_e32 v32, v32
	v_exp_f32_e32 v33, v33
	v_rcp_f32_e32 v30, v30
	v_rcp_f32_e32 v31, v31
	v_add_f32_e32 v32, 1.0, v32
	v_add_f32_e32 v33, 1.0, v33
	v_rcp_f32_e32 v32, v32
	v_rcp_f32_e32 v33, v33
	v_pk_mul_f32 v[26:27], v[26:27], v[30:31]
	v_pk_fma_f32 v[18:19], v[18:19], v[176:177], v[130:131] op_sel_hi:[1,0,1]
	v_pk_fma_f32 v[20:21], v[20:21], v[176:177], v[132:133] op_sel_hi:[1,0,1]
	v_pk_mul_f32 v[26:27], v[18:19], v[26:27]
	v_pk_mul_f32 v[18:19], v[28:29], v[32:33]
	v_pk_fma_f32 v[14:15], v[14:15], v[172:173], v[142:143] op_sel_hi:[1,0,1]
	v_pk_mul_f32 v[28:29], v[20:21], v[18:19]
	v_mad_i64_i32 v[18:19], s[18:19], v174, s56, v[166:167]
	v_lshl_add_u64 v[18:19], v[18:19], 0, s[16:17]
	v_lshl_add_u64 v[30:31], v[18:19], 0, v[154:155]
	v_cvt_pk_bf16_f32 v18, v22, v23
	v_cvt_pk_bf16_f32 v19, v24, v25
	v_cvt_pk_bf16_f32 v20, v26, v27
	v_cvt_pk_bf16_f32 v21, v28, v29
	v_mul_f32_e32 v22, 0xbfb8aa3b, v14
	v_mul_f32_e32 v23, 0xbfb8aa3b, v15
	v_pk_fma_f32 v[16:17], v[16:17], v[172:173], v[144:145] op_sel_hi:[1,0,1]
	v_exp_f32_e32 v22, v22
	v_exp_f32_e32 v23, v23
	global_store_dwordx4 v[30:31], v[18:21], off nt
	v_pk_fma_f32 v[6:7], v[6:7], v[172:173], v[138:139] op_sel_hi:[1,0,1]
	v_pk_fma_f32 v[10:11], v[10:11], v[172:173], v[134:135] op_sel_hi:[1,0,1]
	v_mul_f32_e32 v20, 0xbfb8aa3b, v16
	v_mul_f32_e32 v21, 0xbfb8aa3b, v17
	v_exp_f32_e32 v20, v20
	v_exp_f32_e32 v21, v21
	v_add_f32_e32 v18, 1.0, v22
	v_add_f32_e32 v19, 1.0, v23
	v_rcp_f32_e32 v18, v18
	v_rcp_f32_e32 v19, v19
	v_add_f32_e32 v20, 1.0, v20
	v_add_f32_e32 v21, 1.0, v21
	v_rcp_f32_e32 v20, v20
	v_rcp_f32_e32 v21, v21
	v_pk_mul_f32 v[14:15], v[14:15], v[18:19]
	v_pk_fma_f32 v[8:9], v[8:9], v[172:173], v[140:141] op_sel_hi:[1,0,1]
	v_pk_mul_f32 v[6:7], v[6:7], v[14:15]
	v_pk_mul_f32 v[14:15], v[16:17], v[20:21]
	v_mul_f32_e32 v16, 0xbfb8aa3b, v10
	v_mul_f32_e32 v17, 0xbfb8aa3b, v11
	v_exp_f32_e32 v16, v16
	v_exp_f32_e32 v17, v17
	v_pk_fma_f32 v[12:13], v[12:13], v[172:173], v[136:137] op_sel_hi:[1,0,1]
	v_pk_mul_f32 v[8:9], v[8:9], v[14:15]
	v_add_f32_e32 v14, 1.0, v16
	v_add_f32_e32 v15, 1.0, v17
	v_mul_f32_e32 v16, 0xbfb8aa3b, v12
	v_mul_f32_e32 v17, 0xbfb8aa3b, v13
	v_exp_f32_e32 v16, v16
	v_exp_f32_e32 v17, v17
	v_rcp_f32_e32 v14, v14
	v_rcp_f32_e32 v15, v15
	v_add_f32_e32 v16, 1.0, v16
	v_add_f32_e32 v17, 1.0, v17
	v_rcp_f32_e32 v16, v16
	v_rcp_f32_e32 v17, v17
	v_pk_mul_f32 v[10:11], v[10:11], v[14:15]
	v_pk_fma_f32 v[2:3], v[2:3], v[172:173], v[130:131] op_sel_hi:[1,0,1]
	v_pk_fma_f32 v[4:5], v[4:5], v[172:173], v[132:133] op_sel_hi:[1,0,1]
	v_pk_mul_f32 v[10:11], v[2:3], v[10:11]
	v_pk_mul_f32 v[2:3], v[12:13], v[16:17]
	s_nop 0
	v_pk_mul_f32 v[12:13], v[4:5], v[2:3]
	v_mad_i64_i32 v[2:3], s[18:19], v168, s56, v[166:167]
	v_lshl_add_u64 v[2:3], v[2:3], 0, s[16:17]
	v_lshl_add_u64 v[14:15], v[2:3], 0, v[154:155]
	v_cvt_pk_bf16_f32 v2, v6, v7
	v_cvt_pk_bf16_f32 v3, v8, v9
	v_cvt_pk_bf16_f32 v4, v10, v11
	v_cvt_pk_bf16_f32 v5, v12, v13
	s_mov_b32 s17, s8
	s_mov_b32 s16, s10
	global_store_dwordx4 v[14:15], v[2:5], off nt
	s_cmpk_gt_u32 s33, 0xff
	s_cbranch_scc0 .Ldfr_p12_c
	s_barrier
